# MR: mix phase, odd workgroups process their item list in reverse order (pool, FFT, then attention) so memory-bound and VALU-bound items of different workgroups overlap
# speedup vs baseline: 1.0070x; 1.0070x over previous
; #define LAS __attribute__((address_space(3)))
; __device__ __forceinline__ unsigned pk2(float lo, float hi) { unsigned r; asm volatile("v_cvt_pk_bf16_f32 %0, %1, %2" : "=v"(r) : "v"(lo), "v"(hi)); return r; }
; __device__ __forceinline__ int otid() { int t = threadIdx.x; asm volatile("" : "+v"(t)); return t; }
; __device__ void attn_item(const Params& p, int l, int item, LAS unsigned char* lds) {
;     ...
;     const float sink = p.attn_sink[l * 8 + head] * LOG2E;
;     const float inv = 1.f / (lrun + __builtin_amdgcn_exp2f(sink - mrun));
;     bf16_t* orow = AM + (size_t)(qrow0 + qq) * 1280 + head * 64;
; #pragma unroll
;     for (int dt = 0; dt < 2; ++dt)
; #pragma unroll
;         for (int rq = 0; rq < 4; ++rq) {
;             u32x2 o; o.x = pk2(ot[dt][4 * rq] * inv, ot[dt][4 * rq + 1] * inv); o.y = pk2(ot[dt][4 * rq + 2] * inv, ot[dt][4 * rq + 3] * inv);
;             *(u32x2*)(orow + 32 * dt + 8 * rq + 4 * hi) = o;
;         }
; __device__ void phase_mix(const Params& p, int l, LAS unsigned char* lds) {
;     const int n_attn = (l == 0) ? 544 : 512, n_fft = (l == 0) ? 512 : 256, n_pool = ((l == 0) ? NR : NL) / 16;
;     const int total = n_attn + n_fft + n_pool;
;     { const int tid = otid(); const f32x2* TW = (const f32x2*)(p.ws + OFF_TW); LAS f32x2* tw = (LAS f32x2*)(lds + 65536);
;       for (int i = tid; i < 4095; i += 512) tw[i] = TW[i]; }
;     for (int rep = 0; rep < ((PROBE & 7) && PROBE < 100 ? 2 : 1); ++rep)
;     for (int it = blockIdx.x; it < total; it += gridDim.x) {
;         if (it < n_attn) { if (rep == 0 || (PROBE & 1)) attn_item(p, l, it, lds); }
;         else if (it < n_attn + n_fft) { const int j = it - n_attn; if (rep == 0 || (PROBE & 2)) { if (j < 256) fft_item(p, j, false, lds); else fft_item(p, j - 256, true, lds); } }
;         else { if (rep == 0 || (PROBE & 4)) pool_item(p, it - n_attn - n_fft); }
;     }
.LBB0_33:
	s_or_b64 exec, exec, s[4:5]
	v_readlane_b32 s4, v255, 1
	v_readlane_b32 s5, v255, 2
	s_and_b64 s[4:5], s[4:5], exec
	s_movk_i32 s2, 0x860
	s_cselect_b32 s8, s2, 0x700
	s_cmp_ge_i32 s26, s8
	s_cbranch_scc1 .LBB0_196
	s_mov_b64 s[4:5], 0x6300600
	s_waitcnt lgkmcnt(0)
	v_lshl_add_u64 v[134:135], v[132:133], 0, s[4:5]
	s_mov_b64 s[4:5], 0x6300000
	v_lshl_add_u64 v[136:137], v[132:133], 0, s[4:5]
	s_mov_b64 s[4:5], 0x8d80000
	v_lshl_add_u64 v[138:139], v[132:133], 0, s[4:5]
	v_readlane_b32 s4, v255, 1
	v_readlane_b32 s5, v255, 2
	s_and_b64 s[4:5], s[4:5], exec
	s_movk_i32 s2, 0x220
	s_cselect_b32 s10, s2, 0x200
	s_movk_i32 s2, 0x420
	s_cselect_b32 s12, s2, 0x300
	s_movk_i32 s2, 0xfbe0
	s_cselect_b32 s13, s2, 0xfffffd00
	v_readlane_b32 s2, v255, 0
	s_lshl_b32 s28, s2, 3
	s_mov_b32 s29, s26
	s_bitcmp1_b32 s26, 0
	s_cbranch_scc0 .Lmy_mr_fwd
	s_sub_i32 s4, s8, 1
	s_sub_i32 s4, s4, s26
	s_andn2_b32 s4, s4, 0xff
	s_add_i32 s29, s26, s4
.Lmy_mr_fwd:
	s_branch .LBB0_37
.LBB0_35:
	s_add_i32 s4, s15, s28
	s_ashr_i32 s5, s4, 31
	s_lshl_b64 s[4:5], s[4:5], 2
	v_lshl_add_u64 v[34:35], v[130:131], 0, s[4:5]
	global_load_dword v32, v[34:35], off
	v_readfirstlane_b32 s22, v140
	v_readfirstlane_b32 s23, v141
	v_readfirstlane_b32 s6, v138
	v_readfirstlane_b32 s7, v139
	s_nop 3
	s_add_u32 s22, s22, s6
	s_addc_u32 s23, s23, s7
	s_lshl_b64 s[6:7], s[20:21], 1
	s_add_u32 s22, s22, s6
	s_addc_u32 s23, s23, s7
	v_and_b32_e32 v40, 63, v210
	v_readfirstlane_b32 s6, v210
	v_and_b32_e32 v41, 31, v40
	v_lshrrev_b32_e32 v42, 5, v40
	s_lshr_b32 s6, s6, 6
	s_mul_i32 s6, s6, 0x1200
	s_add_i32 s6, s6, 0x18000
	v_mul_u32_u24_e32 v41, 0x90, v41
	v_lshl_add_u32 v41, v42, 3, v41
	v_add_u32_e32 v41, s6, v41
	v_lshrrev_b32_e32 v42, 3, v40
	v_and_b32_e32 v40, 7, v40
	v_lshlrev_b32_e32 v40, 4, v40
	v_mul_u32_u24_e32 v43, 0x90, v42
	v_add3_u32 v43, v43, v40, s6
	v_mul_u32_u24_e32 v42, 0xa00, v42
	v_add_u32_e32 v42, v42, v40
	s_movk_i32 s31, 0x1ff
	s_movk_i32 s34, 0xfc7f
	s_waitcnt vmcnt(0) lgkmcnt(0)
	v_fma_f32 v32, v32, s30, -v225
	v_exp_f32_e32 v32, v32
	s_nop 0
	v_add_f32_e32 v36, v33, v32
	v_div_scale_f32 v37, s[4:5], v36, v36, 1.0
	v_rcp_f32_e32 v38, v37
	s_nop 0
	v_div_scale_f32 v34, vcc, 1.0, v36, 1.0
	v_fma_f32 v35, -v37, v38, 1.0
	v_fmac_f32_e32 v38, v35, v38
	v_mul_f32_e32 v35, v34, v38
	v_fma_f32 v39, -v37, v35, v34
	v_fmac_f32_e32 v35, v39, v38
	v_fma_f32 v34, -v37, v35, v34
	v_div_fmas_f32 v34, v34, v38, v35
	v_div_fixup_f32 v34, v34, v36, 1.0
	v_mul_f32_e32 v16, v16, v34
	v_mul_f32_e32 v17, v17, v34
	v_mul_f32_e32 v18, v18, v34
	v_mul_f32_e32 v19, v19, v34
	v_mul_f32_e32 v20, v20, v34
	v_mul_f32_e32 v21, v21, v34
	v_mul_f32_e32 v22, v22, v34
	v_mul_f32_e32 v23, v23, v34
	v_mul_f32_e32 v24, v24, v34
	v_mul_f32_e32 v25, v25, v34
	v_mul_f32_e32 v26, v26, v34
	v_mul_f32_e32 v27, v27, v34
	v_mul_f32_e32 v28, v28, v34
	v_mul_f32_e32 v29, v29, v34
	v_mul_f32_e32 v30, v30, v34
	v_mul_f32_e32 v31, v31, v34
	v_mul_f32_e32 v0, v0, v34
	v_mul_f32_e32 v1, v1, v34
	v_mul_f32_e32 v2, v2, v34
	v_mul_f32_e32 v3, v3, v34
	v_mul_f32_e32 v4, v4, v34
	v_mul_f32_e32 v5, v5, v34
	v_mul_f32_e32 v6, v6, v34
	v_mul_f32_e32 v7, v7, v34
	v_mul_f32_e32 v8, v8, v34
	v_mul_f32_e32 v9, v9, v34
	v_mul_f32_e32 v10, v10, v34
	v_mul_f32_e32 v11, v11, v34
	v_mul_f32_e32 v12, v12, v34
	v_mul_f32_e32 v13, v13, v34
	v_mul_f32_e32 v14, v14, v34
	v_mul_f32_e32 v15, v15, v34
	v_cvt_pk_bf16_f32 v48, v16, v17
	v_cvt_pk_bf16_f32 v49, v18, v19
	v_cvt_pk_bf16_f32 v50, v20, v21
	v_cvt_pk_bf16_f32 v51, v22, v23
	v_cvt_pk_bf16_f32 v52, v24, v25
	v_cvt_pk_bf16_f32 v53, v26, v27
	v_cvt_pk_bf16_f32 v54, v28, v29
	v_cvt_pk_bf16_f32 v55, v30, v31
	v_cvt_pk_bf16_f32 v56, v0, v1
	v_cvt_pk_bf16_f32 v57, v2, v3
	v_cvt_pk_bf16_f32 v58, v4, v5
	v_cvt_pk_bf16_f32 v59, v6, v7
	v_cvt_pk_bf16_f32 v60, v8, v9
	v_cvt_pk_bf16_f32 v61, v10, v11
	v_cvt_pk_bf16_f32 v62, v12, v13
	v_cvt_pk_bf16_f32 v63, v14, v15
	ds_write_b64 v41, v[48:49]
	ds_write_b64 v41, v[50:51] offset:16
	ds_write_b64 v41, v[52:53] offset:32
	ds_write_b64 v41, v[54:55] offset:48
	ds_write_b64 v41, v[56:57] offset:64
	ds_write_b64 v41, v[58:59] offset:80
	ds_write_b64 v41, v[60:61] offset:96
	ds_write_b64 v41, v[62:63] offset:112
	s_waitcnt lgkmcnt(0)
	ds_read_b128 v[48:51], v43
	ds_read_b128 v[52:55], v43 offset:1152
	ds_read_b128 v[56:59], v43 offset:2304
	ds_read_b128 v[60:63], v43 offset:3456
	s_waitcnt lgkmcnt(3)
	global_store_dwordx4 v42, v[48:51], s[22:23]
	s_add_u32 s22, s22, 0x5000
	s_addc_u32 s23, s23, 0
	s_waitcnt lgkmcnt(2)
	global_store_dwordx4 v42, v[52:55], s[22:23]
	s_add_u32 s22, s22, 0x5000
	s_addc_u32 s23, s23, 0
	s_waitcnt lgkmcnt(1)
	global_store_dwordx4 v42, v[56:59], s[22:23]
	s_add_u32 s22, s22, 0x5000
	s_addc_u32 s23, s23, 0
	s_waitcnt lgkmcnt(0)
	global_store_dwordx4 v42, v[60:63], s[22:23]
.LBB0_36:
	s_bitcmp1_b32 s26, 0
	s_cbranch_scc1 .Lmy_mr_rev
	s_add_i32 s29, s29, s72
	s_cmp_ge_i32 s29, s8
	s_cbranch_scc1 .LBB0_196
	s_branch .LBB0_37
.Lmy_mr_rev:
	s_sub_i32 s29, s29, s72
	s_cmp_lt_i32 s29, 0
	s_cbranch_scc1 .LBB0_196
